# init_rows chunks assigned statically (no per-chunk atomic), adaLN GEMM epilogue rewritten without per-fragment waits, skinny residual epilogue parameter loads issued together
# speedup vs baseline: 1.0274x; 1.0121x over previous
.LBB0_779:
	s_load_dwordx2 s[40:41], s[0:1], 0x40
	s_load_dwordx2 s[12:13], s[0:1], 0x80
	s_mov_b32 s10, -1
	s_mov_b32 s11, 0x1a000
	v_lshlrev_b32_e32 v130, 2, v168
	v_mov_b32_e32 v131, 0
	v_and_b32_e32 v190, 0x3ff, v168
	v_mov_b32_e32 v191, 0
	v_mov_b32_e32 v149, 0
	v_lshlrev_b32_e32 v190, 1, v190
	s_cmp_lt_u32 s42, 0x6000
	s_cbranch_scc0 .Lada_kv
	s_cmp_ge_u32 s42, 0x1800
	s_cselect_b32 s8, 1, 0
	s_cmp_ge_u32 s42, 0x3000
	s_cselect_b32 s9, 1, 0
	s_add_u32 s8, s8, s9
	s_cmp_ge_u32 s42, 0x4800
	s_cselect_b32 s9, 1, 0
	s_add_u32 s8, s8, s9
	s_mul_i32 s9, s8, 0x1800
	s_sub_u32 s9, s42, s9
	s_lshr_b32 s9, s9, 10
	s_cmp_eq_u32 s9, 0
	s_cselect_b32 s10, s8, s10
	s_add_u32 s8, s8, 5
	s_cmp_eq_u32 s9, 3
	s_cselect_b32 s10, s8, s10
	s_waitcnt lgkmcnt(0)
	s_branch .Lada_go
.Lada_kv:
	s_cmp_lt_u32 s42, 0x6400
	s_cselect_b32 s10, 4, -1
	s_waitcnt lgkmcnt(0)
	s_add_u32 s40, s12, 0xfffe8000
	s_addc_u32 s41, s13, -1
.Lada_go:
	global_load_dwordx4 v[132:135], v130, s[40:41]
	global_load_dwordx4 v[136:139], v130, s[40:41] offset:16
	global_load_dwordx4 v[140:143], v130, s[40:41] offset:512
	global_load_dwordx4 v[144:147], v130, s[40:41] offset:528
	v_lshl_add_u64 v[154:155], s[18:19], 0, v[130:131]
	s_max_i32 s8, s10, 0
	s_lshl_b32 s8, s8, 19
	s_add_u32 s12, s56, s8
	s_addc_u32 s13, s57, 0
	v_lshl_add_u64 v[186:187], s[12:13], 0, v[190:191]
	s_waitcnt vmcnt(0)
	v_add_u32_e32 v150, 0, v170
	v_cmp_gt_i32_e32 vcc, s53, v150
	s_and_saveexec_b64 s[8:9], vcc
	s_cbranch_execz .Lada_r0
	v_mad_u64_u32 v[152:153], vcc, v150, s11, v[154:155]
	v_lshlrev_b32_e32 v148, 11, v150
	v_lshl_add_u64 v[188:189], v[148:149], 0, v[186:187]
	v_pk_add_f32 v[156:157], v[104:105], v[132:133]
	v_pk_add_f32 v[158:159], v[106:107], v[134:135]
	v_pk_add_f32 v[160:161], v[96:97], v[136:137]
	v_pk_add_f32 v[162:163], v[98:99], v[138:139]
	global_store_dwordx4 v[152:153], v[156:159], off
	global_store_dwordx4 v[152:153], v[160:163], off offset:16
	s_cmp_lt_i32 s10, 0
	s_cbranch_scc1 .Lada_n0_0
	v_cvt_pk_bf16_f32 v164, v156, v157
	v_cvt_pk_bf16_f32 v165, v158, v159
	v_cvt_pk_bf16_f32 v166, v160, v161
	v_cvt_pk_bf16_f32 v167, v162, v163
	global_store_dwordx4 v[188:189], v[164:167], off
.Lada_n0_0:
	v_pk_add_f32 v[172:173], v[44:45], v[140:141]
	v_pk_add_f32 v[174:175], v[46:47], v[142:143]
	v_pk_add_f32 v[176:177], v[40:41], v[144:145]
	v_pk_add_f32 v[178:179], v[42:43], v[146:147]
	global_store_dwordx4 v[152:153], v[172:175], off offset:512
	global_store_dwordx4 v[152:153], v[176:179], off offset:528
	s_cmp_lt_i32 s10, 0
	s_cbranch_scc1 .Lada_n0_1
	v_cvt_pk_bf16_f32 v180, v172, v173
	v_cvt_pk_bf16_f32 v181, v174, v175
	v_cvt_pk_bf16_f32 v182, v176, v177
	v_cvt_pk_bf16_f32 v183, v178, v179
	global_store_dwordx4 v[188:189], v[180:183], off offset:256
.Lada_n0_1:
.Lada_r0:
	s_or_b64 exec, exec, s[8:9]
	v_add_u32_e32 v150, 16, v170
	v_cmp_gt_i32_e32 vcc, s53, v150
	s_and_saveexec_b64 s[8:9], vcc
	s_cbranch_execz .Lada_r1
	v_mad_u64_u32 v[152:153], vcc, v150, s11, v[154:155]
	v_lshlrev_b32_e32 v148, 11, v150
	v_lshl_add_u64 v[188:189], v[148:149], 0, v[186:187]
	v_pk_add_f32 v[156:157], v[88:89], v[132:133]
	v_pk_add_f32 v[158:159], v[90:91], v[134:135]
	v_pk_add_f32 v[160:161], v[80:81], v[136:137]
	v_pk_add_f32 v[162:163], v[82:83], v[138:139]
	global_store_dwordx4 v[152:153], v[156:159], off
	global_store_dwordx4 v[152:153], v[160:163], off offset:16
	s_cmp_lt_i32 s10, 0
	s_cbranch_scc1 .Lada_n1_0
	v_cvt_pk_bf16_f32 v164, v156, v157
	v_cvt_pk_bf16_f32 v165, v158, v159
	v_cvt_pk_bf16_f32 v166, v160, v161
	v_cvt_pk_bf16_f32 v167, v162, v163
	global_store_dwordx4 v[188:189], v[164:167], off
.Lada_n1_0:
	v_pk_add_f32 v[172:173], v[36:37], v[140:141]
	v_pk_add_f32 v[174:175], v[38:39], v[142:143]
	v_pk_add_f32 v[176:177], v[32:33], v[144:145]
	v_pk_add_f32 v[178:179], v[34:35], v[146:147]
	global_store_dwordx4 v[152:153], v[172:175], off offset:512
	global_store_dwordx4 v[152:153], v[176:179], off offset:528
	s_cmp_lt_i32 s10, 0
	s_cbranch_scc1 .Lada_n1_1
	v_cvt_pk_bf16_f32 v180, v172, v173
	v_cvt_pk_bf16_f32 v181, v174, v175
	v_cvt_pk_bf16_f32 v182, v176, v177
	v_cvt_pk_bf16_f32 v183, v178, v179
	global_store_dwordx4 v[188:189], v[180:183], off offset:256
.Lada_n1_1:
.Lada_r1:
	s_or_b64 exec, exec, s[8:9]
	v_add_u32_e32 v150, 32, v170
	v_cmp_gt_i32_e32 vcc, s53, v150
	s_and_saveexec_b64 s[8:9], vcc
	s_cbranch_execz .Lada_r2
	v_mad_u64_u32 v[152:153], vcc, v150, s11, v[154:155]
	v_lshlrev_b32_e32 v148, 11, v150
	v_lshl_add_u64 v[188:189], v[148:149], 0, v[186:187]
	v_pk_add_f32 v[156:157], v[72:73], v[132:133]
	v_pk_add_f32 v[158:159], v[74:75], v[134:135]
	v_pk_add_f32 v[160:161], v[64:65], v[136:137]
	v_pk_add_f32 v[162:163], v[66:67], v[138:139]
	global_store_dwordx4 v[152:153], v[156:159], off
	global_store_dwordx4 v[152:153], v[160:163], off offset:16
	s_cmp_lt_i32 s10, 0
	s_cbranch_scc1 .Lada_n2_0
	v_cvt_pk_bf16_f32 v164, v156, v157
	v_cvt_pk_bf16_f32 v165, v158, v159
	v_cvt_pk_bf16_f32 v166, v160, v161
	v_cvt_pk_bf16_f32 v167, v162, v163
	global_store_dwordx4 v[188:189], v[164:167], off
.Lada_n2_0:
	v_pk_add_f32 v[172:173], v[28:29], v[140:141]
	v_pk_add_f32 v[174:175], v[30:31], v[142:143]
	v_pk_add_f32 v[176:177], v[24:25], v[144:145]
	v_pk_add_f32 v[178:179], v[26:27], v[146:147]
	global_store_dwordx4 v[152:153], v[172:175], off offset:512
	global_store_dwordx4 v[152:153], v[176:179], off offset:528
	s_cmp_lt_i32 s10, 0
	s_cbranch_scc1 .Lada_n2_1
	v_cvt_pk_bf16_f32 v180, v172, v173
	v_cvt_pk_bf16_f32 v181, v174, v175
	v_cvt_pk_bf16_f32 v182, v176, v177
	v_cvt_pk_bf16_f32 v183, v178, v179
	global_store_dwordx4 v[188:189], v[180:183], off offset:256
.Lada_n2_1:
.Lada_r2:
	s_or_b64 exec, exec, s[8:9]
	v_add_u32_e32 v150, 48, v170
	v_cmp_gt_i32_e32 vcc, s53, v150
	s_and_saveexec_b64 s[8:9], vcc
	s_cbranch_execz .Lada_r3
	v_mad_u64_u32 v[152:153], vcc, v150, s11, v[154:155]
	v_lshlrev_b32_e32 v148, 11, v150
	v_lshl_add_u64 v[188:189], v[148:149], 0, v[186:187]
	v_pk_add_f32 v[156:157], v[56:57], v[132:133]
	v_pk_add_f32 v[158:159], v[58:59], v[134:135]
	v_pk_add_f32 v[160:161], v[48:49], v[136:137]
	v_pk_add_f32 v[162:163], v[50:51], v[138:139]
	global_store_dwordx4 v[152:153], v[156:159], off
	global_store_dwordx4 v[152:153], v[160:163], off offset:16
	s_cmp_lt_i32 s10, 0
	s_cbranch_scc1 .Lada_n3_0
	v_cvt_pk_bf16_f32 v164, v156, v157
	v_cvt_pk_bf16_f32 v165, v158, v159
	v_cvt_pk_bf16_f32 v166, v160, v161
	v_cvt_pk_bf16_f32 v167, v162, v163
	global_store_dwordx4 v[188:189], v[164:167], off
.Lada_n3_0:
	v_pk_add_f32 v[172:173], v[20:21], v[140:141]
	v_pk_add_f32 v[174:175], v[22:23], v[142:143]
	v_pk_add_f32 v[176:177], v[16:17], v[144:145]
	v_pk_add_f32 v[178:179], v[18:19], v[146:147]
	global_store_dwordx4 v[152:153], v[172:175], off offset:512
	global_store_dwordx4 v[152:153], v[176:179], off offset:528
	s_cmp_lt_i32 s10, 0
	s_cbranch_scc1 .Lada_n3_1
	v_cvt_pk_bf16_f32 v180, v172, v173
	v_cvt_pk_bf16_f32 v181, v174, v175
	v_cvt_pk_bf16_f32 v182, v176, v177
	v_cvt_pk_bf16_f32 v183, v178, v179
	global_store_dwordx4 v[188:189], v[180:183], off offset:256
.Lada_n3_1:
.Lada_r3:
	s_or_b64 exec, exec, s[8:9]
	v_add_u32_e32 v150, 0x80, v170
	v_cmp_gt_i32_e32 vcc, s53, v150
	s_and_saveexec_b64 s[8:9], vcc
	s_cbranch_execz .Lada_r4
	v_mad_u64_u32 v[152:153], vcc, v150, s11, v[154:155]
	v_lshlrev_b32_e32 v148, 11, v150
	v_lshl_add_u64 v[188:189], v[148:149], 0, v[186:187]
	v_pk_add_f32 v[156:157], v[12:13], v[132:133]
	v_pk_add_f32 v[158:159], v[14:15], v[134:135]
	v_pk_add_f32 v[160:161], v[8:9], v[136:137]
	v_pk_add_f32 v[162:163], v[10:11], v[138:139]
	global_store_dwordx4 v[152:153], v[156:159], off
	global_store_dwordx4 v[152:153], v[160:163], off offset:16
	s_cmp_lt_i32 s10, 0
	s_cbranch_scc1 .Lada_n4_0
	v_cvt_pk_bf16_f32 v164, v156, v157
	v_cvt_pk_bf16_f32 v165, v158, v159
	v_cvt_pk_bf16_f32 v166, v160, v161
	v_cvt_pk_bf16_f32 v167, v162, v163
	global_store_dwordx4 v[188:189], v[164:167], off
.Lada_n4_0:
	v_pk_add_f32 v[172:173], v[84:85], v[140:141]
	v_pk_add_f32 v[174:175], v[86:87], v[142:143]
	v_pk_add_f32 v[176:177], v[92:93], v[144:145]
	v_pk_add_f32 v[178:179], v[94:95], v[146:147]
	global_store_dwordx4 v[152:153], v[172:175], off offset:512
	global_store_dwordx4 v[152:153], v[176:179], off offset:528
	s_cmp_lt_i32 s10, 0
	s_cbranch_scc1 .Lada_n4_1
	v_cvt_pk_bf16_f32 v180, v172, v173
	v_cvt_pk_bf16_f32 v181, v174, v175
	v_cvt_pk_bf16_f32 v182, v176, v177
	v_cvt_pk_bf16_f32 v183, v178, v179
	global_store_dwordx4 v[188:189], v[180:183], off offset:256
.Lada_n4_1:
.Lada_r4:
	s_or_b64 exec, exec, s[8:9]
	v_add_u32_e32 v150, 0x90, v170
	v_cmp_gt_i32_e32 vcc, s53, v150
	s_and_saveexec_b64 s[8:9], vcc
	s_cbranch_execz .Lada_r5
	v_mad_u64_u32 v[152:153], vcc, v150, s11, v[154:155]
	v_lshlrev_b32_e32 v148, 11, v150
	v_lshl_add_u64 v[188:189], v[148:149], 0, v[186:187]
	v_pk_add_f32 v[156:157], v[4:5], v[132:133]
	v_pk_add_f32 v[158:159], v[6:7], v[134:135]
	v_pk_add_f32 v[160:161], v[0:1], v[136:137]
	v_pk_add_f32 v[162:163], v[2:3], v[138:139]
	global_store_dwordx4 v[152:153], v[156:159], off
	global_store_dwordx4 v[152:153], v[160:163], off offset:16
	s_cmp_lt_i32 s10, 0
	s_cbranch_scc1 .Lada_n5_0
	v_cvt_pk_bf16_f32 v164, v156, v157
	v_cvt_pk_bf16_f32 v165, v158, v159
	v_cvt_pk_bf16_f32 v166, v160, v161
	v_cvt_pk_bf16_f32 v167, v162, v163
	global_store_dwordx4 v[188:189], v[164:167], off
.Lada_n5_0:
	v_pk_add_f32 v[172:173], v[100:101], v[140:141]
	v_pk_add_f32 v[174:175], v[102:103], v[142:143]
	v_pk_add_f32 v[176:177], v[108:109], v[144:145]
	v_pk_add_f32 v[178:179], v[110:111], v[146:147]
	global_store_dwordx4 v[152:153], v[172:175], off offset:512
	global_store_dwordx4 v[152:153], v[176:179], off offset:528
	s_cmp_lt_i32 s10, 0
	s_cbranch_scc1 .Lada_n5_1
	v_cvt_pk_bf16_f32 v180, v172, v173
	v_cvt_pk_bf16_f32 v181, v174, v175
	v_cvt_pk_bf16_f32 v182, v176, v177
	v_cvt_pk_bf16_f32 v183, v178, v179
	global_store_dwordx4 v[188:189], v[180:183], off offset:256
.Lada_n5_1:
.Lada_r5:
	s_or_b64 exec, exec, s[8:9]
	v_add_u32_e32 v150, 0xa0, v170
	v_cmp_gt_i32_e32 vcc, s53, v150
	s_and_saveexec_b64 s[8:9], vcc
	s_cbranch_execz .Lada_r6
	v_mad_u64_u32 v[152:153], vcc, v150, s11, v[154:155]
	v_lshlrev_b32_e32 v148, 11, v150
	v_lshl_add_u64 v[188:189], v[148:149], 0, v[186:187]
	v_pk_add_f32 v[156:157], v[52:53], v[132:133]
	v_pk_add_f32 v[158:159], v[54:55], v[134:135]
	v_pk_add_f32 v[160:161], v[60:61], v[136:137]
	v_pk_add_f32 v[162:163], v[62:63], v[138:139]
	global_store_dwordx4 v[152:153], v[156:159], off
	global_store_dwordx4 v[152:153], v[160:163], off offset:16
	s_cmp_lt_i32 s10, 0
	s_cbranch_scc1 .Lada_n6_0
	v_cvt_pk_bf16_f32 v164, v156, v157
	v_cvt_pk_bf16_f32 v165, v158, v159
	v_cvt_pk_bf16_f32 v166, v160, v161
	v_cvt_pk_bf16_f32 v167, v162, v163
	global_store_dwordx4 v[188:189], v[164:167], off
.Lada_n6_0:
	v_pk_add_f32 v[172:173], v[112:113], v[140:141]
	v_pk_add_f32 v[174:175], v[114:115], v[142:143]
	v_pk_add_f32 v[176:177], v[116:117], v[144:145]
	v_pk_add_f32 v[178:179], v[118:119], v[146:147]
	global_store_dwordx4 v[152:153], v[172:175], off offset:512
	global_store_dwordx4 v[152:153], v[176:179], off offset:528
	s_cmp_lt_i32 s10, 0
	s_cbranch_scc1 .Lada_n6_1
	v_cvt_pk_bf16_f32 v180, v172, v173
	v_cvt_pk_bf16_f32 v181, v174, v175
	v_cvt_pk_bf16_f32 v182, v176, v177
	v_cvt_pk_bf16_f32 v183, v178, v179
	global_store_dwordx4 v[188:189], v[180:183], off offset:256
.Lada_n6_1:
.Lada_r6:
	s_or_b64 exec, exec, s[8:9]
	v_add_u32_e32 v150, 0xb0, v170
	v_cmp_gt_i32_e32 vcc, s53, v150
	s_and_saveexec_b64 s[8:9], vcc
	s_cbranch_execz .Lada_r7
	v_mad_u64_u32 v[152:153], vcc, v150, s11, v[154:155]
	v_lshlrev_b32_e32 v148, 11, v150
	v_lshl_add_u64 v[188:189], v[148:149], 0, v[186:187]
	v_pk_add_f32 v[156:157], v[68:69], v[132:133]
	v_pk_add_f32 v[158:159], v[70:71], v[134:135]
	v_pk_add_f32 v[160:161], v[76:77], v[136:137]
	v_pk_add_f32 v[162:163], v[78:79], v[138:139]
	global_store_dwordx4 v[152:153], v[156:159], off
	global_store_dwordx4 v[152:153], v[160:163], off offset:16
	s_cmp_lt_i32 s10, 0
	s_cbranch_scc1 .Lada_n7_0
	v_cvt_pk_bf16_f32 v164, v156, v157
	v_cvt_pk_bf16_f32 v165, v158, v159
	v_cvt_pk_bf16_f32 v166, v160, v161
	v_cvt_pk_bf16_f32 v167, v162, v163
	global_store_dwordx4 v[188:189], v[164:167], off
.Lada_n7_0:
	v_pk_add_f32 v[172:173], v[120:121], v[140:141]
	v_pk_add_f32 v[174:175], v[122:123], v[142:143]
	v_pk_add_f32 v[176:177], v[124:125], v[144:145]
	v_pk_add_f32 v[178:179], v[126:127], v[146:147]
	global_store_dwordx4 v[152:153], v[172:175], off offset:512
	global_store_dwordx4 v[152:153], v[176:179], off offset:528
	s_cmp_lt_i32 s10, 0
	s_cbranch_scc1 .Lada_n7_1
	v_cvt_pk_bf16_f32 v180, v172, v173
	v_cvt_pk_bf16_f32 v181, v174, v175
	v_cvt_pk_bf16_f32 v182, v176, v177
	v_cvt_pk_bf16_f32 v183, v178, v179
	global_store_dwordx4 v[188:189], v[180:183], off offset:256
.Lada_n7_1:
.Lada_r7:
	s_or_b64 exec, exec, s[8:9]
	s_mov_b64 s[8:9], -1

.LBB0_931:
	v_readlane_b32 s8, v254, 40
	v_readlane_b32 s9, v254, 41
	s_andn2_b64 vcc, exec, s[8:9]
	s_cbranch_vccnz .LBB0_377
	s_barrier
	s_branch .LBB0_377
.LBB0_951:
	v_readlane_b32 s66, v254, 1
	v_readlane_b32 s52, v253, 61
	v_readlane_b32 s67, v254, 2
	v_readlane_b32 s50, v254, 22
	v_readlane_b32 s53, v253, 62
	v_readlane_b32 s68, v254, 3
	v_readlane_b32 s69, v254, 4
	s_movk_i32 s70, 0x1000
	v_readlane_b32 s44, v254, 8
	v_readlane_b32 s45, v254, 9
	s_mov_b32 s71, 0x20000
	s_mov_b32 s73, 0x1ffff
	s_mov_b32 s87, 0x800000
	s_mov_b32 s74, 0x50000
	s_mov_b32 s75, 0xe000
	s_movk_i32 s78, 0x3000
	s_movk_i32 s79, 0x5000
	s_movk_i32 s80, 0x7000
	s_mov_b32 s81, 0x8000
	s_mov_b32 s59, 0xa000
	s_mov_b32 s67, 0xc000
	s_mov_b32 s64, 0xf000
	v_readlane_b32 s51, v254, 23
	v_readlane_b32 s62, v254, 49
	v_readlane_b32 s86, v254, 38
	v_readlane_b32 s82, v254, 45
	v_readlane_b32 s34, v255, 17
	s_barrier
	v_readlane_b32 s83, v254, 46

.LBB0_994:
	v_cmp_gt_i32_e32 vcc, s5, v8
	v_ashrrev_i32_e32 v6, 12, v8
	v_add_u32_e32 v7, 0xffffc004, v8
	v_cndmask_b32_e32 v6, v7, v6, vcc
	s_movk_i32 s35, 0x6800
	v_mad_i64_i32 v[14:15], s[36:37], v6, s35, 0
	v_readlane_b32 s36, v255, 15
	v_ashrrev_i32_e32 v11, 31, v10
	v_readlane_b32 s37, v255, 16
	v_lshlrev_b64 v[16:17], 2, v[10:11]
	v_lshl_add_u64 v[4:5], v[4:5], 0, v[16:17]
	v_lshl_add_u64 v[18:19], v[14:15], 2, s[36:37]
	v_lshl_add_u64 v[18:19], v[18:19], 0, v[16:17]
	global_load_dwordx4 v[4:7], v[4:5], off
	s_andn2_b64 vcc, exec, s[6:7]
	global_load_dwordx4 v[18:21], v[18:19], off
	s_cbranch_vccnz .Lsr_nopre
	v_readlane_b32 s36, v255, 3
	v_readlane_b32 s37, v255, 4
	s_nop 1
	v_lshl_add_u64 v[50:51], s[36:37], 0, v[16:17]
	v_readlane_b32 s36, v255, 1
	v_readlane_b32 s37, v255, 2
	global_load_dwordx4 v[50:53], v[50:51], off
	s_nop 0
	v_lshl_add_u64 v[54:55], v[14:15], 2, s[36:37]
	v_lshl_add_u64 v[54:55], v[54:55], 0, v[16:17]
	global_load_dwordx4 v[54:57], v[54:55], off
	s_cmp_lg_u64 s[8:9], 0
	s_cbranch_scc0 .Lsr_nopre
	v_readlane_b32 s36, v254, 59
	v_readlane_b32 s37, v254, 60
	s_nop 1
	v_lshl_add_u64 v[58:59], s[36:37], 0, v[16:17]
	v_readlane_b32 s36, v254, 61
	v_readlane_b32 s37, v254, 62
	global_load_dwordx4 v[58:61], v[58:59], off
	s_nop 0
	v_lshl_add_u64 v[62:63], v[14:15], 2, s[36:37]
	v_lshl_add_u64 v[62:63], v[62:63], 0, v[16:17]
	global_load_dwordx4 v[62:65], v[62:63], off
.Lsr_nopre:
	s_waitcnt vmcnt(0)
	v_pk_fma_f32 v[4:5], v[0:1], v[18:19], v[4:5]
	v_lshlrev_b64 v[18:19], 12, v[12:13]
	v_lshl_add_u64 v[18:19], s[18:19], 0, v[18:19]
	v_pk_fma_f32 v[6:7], v[2:3], v[20:21], v[6:7]
	v_lshl_add_u64 v[18:19], v[18:19], 0, v[16:17]
	global_store_dwordx4 v[18:19], v[4:7], off
	s_cbranch_vccnz .LBB0_1000
	v_readlane_b32 s36, v255, 3
	v_readlane_b32 s37, v255, 4
	v_lshlrev_b64 v[18:19], 10, v[12:13]
	s_andn2_b64 vcc, exec, s[8:9]
	v_readlane_b32 s36, v255, 1
	v_readlane_b32 s37, v255, 2
	v_pk_mul_f32 v[22:23], v[6:7], v[52:53]
	v_pk_mul_f32 v[20:21], v[4:5], v[50:51]
	v_pk_add_f32 v[26:27], v[56:57], 1.0 op_sel_hi:[1,0]
	v_pk_add_f32 v[24:25], v[54:55], 1.0 op_sel_hi:[1,0]
	v_pk_mul_f32 v[22:23], v[22:23], v[26:27]
	v_pk_mul_f32 v[20:21], v[20:21], v[24:25]
	s_nop 0
	v_cvt_pk_bf16_f32 v20, v20, v21
	v_cvt_pk_bf16_f32 v21, v22, v23
	v_lshl_add_u64 v[22:23], v[18:19], 1, s[46:47]
	v_lshl_add_u64 v[22:23], v[10:11], 1, v[22:23]
	global_store_dwordx2 v[22:23], v[20:21], off
	s_cbranch_vccnz .LBB0_997
	v_readlane_b32 s36, v254, 59
	v_readlane_b32 s37, v254, 60
	s_nop 1
	v_readlane_b32 s36, v254, 61
	v_readlane_b32 s37, v254, 62
	v_pk_mul_f32 v[22:23], v[6:7], v[60:61]
	v_readlane_b32 s36, v254, 63
	v_readlane_b32 s37, v255, 0
	v_pk_mul_f32 v[20:21], v[4:5], v[58:59]
	v_pk_add_f32 v[16:17], v[64:65], 1.0 op_sel_hi:[1,0]
	v_pk_add_f32 v[14:15], v[62:63], 1.0 op_sel_hi:[1,0]
	v_lshl_add_u64 v[18:19], v[18:19], 1, s[36:37]
	v_pk_mul_f32 v[16:17], v[22:23], v[16:17]
	v_pk_mul_f32 v[14:15], v[20:21], v[14:15]
	s_nop 0
	v_cvt_pk_bf16_f32 v14, v14, v15
	v_cvt_pk_bf16_f32 v15, v16, v17
	v_lshl_add_u64 v[16:17], v[10:11], 1, v[18:19]
	global_store_dwordx2 v[16:17], v[14:15], off

.LBB0_1147:
	v_mov_b32_e32 v0, v220
	s_load_dwordx2 s[8:9], s[0:1], 0x48
	v_and_b32_e32 v2, 63, v0
	v_lshlrev_b32_e32 v192, 4, v2
	s_waitcnt lgkmcnt(0)
	v_lshl_add_u64 v[0:1], s[16:17], 0, v[192:193]
	s_add_u32 s2, s16, 0x1b06c790
	v_lshl_add_u64 v[66:67], s[8:9], 0, v[192:193]
	s_mov_b64 s[8:9], 0x5d01000
	v_lshl_add_u64 v[68:69], v[0:1], 0, s[8:9]
	v_readlane_b32 s8, v254, 55
	v_lshlrev_b32_e32 v192, 3, v2
	v_readlane_b32 s9, v254, 56
	s_addc_u32 s3, s17, 0
	v_cmp_eq_u32_e64 s[6:7], 0, v2
	v_lshlrev_b32_e32 v64, 2, v2
	v_lshl_add_u64 v[70:71], s[8:9], 0, v[192:193]
	v_readlane_b32 s98, v253, 0
	v_readlane_b32 s99, v253, 63
	s_mov_b32 s101, 0
	s_cmpk_eq_u32 s99, 0x100
	s_cbranch_scc0 .LBB0_1150
	s_cmpk_lt_u32 s98, 0x6a
	s_cbranch_scc1 .LBB0_1131
	s_sub_u32 s98, s98, 0x6a
	s_lshl_b32 s98, s98, 3
	v_readfirstlane_b32 s100, v220
	s_nop 0
	s_lshr_b32 s100, s100, 6
	s_add_u32 s100, s100, s98
	s_movk_i32 s101, 0x4b0
	s_branch .LBB0_1150

.LBB0_1150:
	s_cmp_eq_u32 s101, 0
	s_cbranch_scc1 .Linit_dyn
	v_mov_b32_e32 v0, s100
	s_add_u32 s100, s100, s101
	s_branch .Linit_join

.Linit_join:
	v_readfirstlane_b32 s12, v0
	s_cmpk_gt_u32 s12, 0x80f
	s_mov_b64 s[8:9], -1
	s_cbranch_scc1 .LBB0_1149
	v_and_b32_e32 v0, 64, v232
	v_add_u32_e32 v0, 64, v0
	v_xor_b32_e32 v1, 1, v232
	v_cmp_lt_i32_e32 vcc, v1, v0
	s_lshl_b32 s24, s12, 3
	s_lshr_b32 s25, s12, 9
	v_cndmask_b32_e32 v1, v232, v1, vcc
	v_lshlrev_b32_e32 v65, 2, v1
	v_xor_b32_e32 v1, 2, v232
	v_cmp_lt_i32_e32 vcc, v1, v0
	s_cmpk_lt_u32 s12, 0x800
	s_cselect_b64 s[10:11], -1, 0
	v_cndmask_b32_e32 v1, v232, v1, vcc
	v_lshlrev_b32_e32 v72, 2, v1
	v_xor_b32_e32 v1, 4, v232
	v_cmp_lt_i32_e32 vcc, v1, v0
	s_cmpk_gt_u32 s12, 0x7ff
	s_mov_b32 s8, 0
	v_cndmask_b32_e32 v1, v232, v1, vcc
	v_lshlrev_b32_e32 v73, 2, v1
	v_xor_b32_e32 v1, 8, v232
	v_cmp_lt_i32_e32 vcc, v1, v0
	s_cselect_b64 s[12:13], -1, 0
	s_mov_b64 s[14:15], -1
	v_cndmask_b32_e32 v1, v232, v1, vcc
	v_lshlrev_b32_e32 v74, 2, v1
	v_xor_b32_e32 v1, 16, v232
	v_cmp_lt_i32_e32 vcc, v1, v0
	s_nop 1
	v_cndmask_b32_e32 v1, v232, v1, vcc
	v_lshlrev_b32_e32 v75, 2, v1
	v_xor_b32_e32 v1, 32, v232
	v_cmp_lt_i32_e32 vcc, v1, v0
	s_nop 1
	v_cndmask_b32_e32 v0, v232, v1, vcc
	v_lshlrev_b32_e32 v76, 2, v0
	s_branch .LBB0_1157

	.amdhsa_kernel _Z8yoco_fwd1P
		.amdhsa_group_segment_fixed_size 0
		.amdhsa_private_segment_fixed_size 0
		.amdhsa_kernarg_size 480
		.amdhsa_user_sgpr_count 2
		.amdhsa_user_sgpr_dispatch_ptr 0
		.amdhsa_user_sgpr_queue_ptr 0
		.amdhsa_user_sgpr_kernarg_segment_ptr 1
		.amdhsa_user_sgpr_dispatch_id 0
		.amdhsa_user_sgpr_kernarg_preload_length 0
		.amdhsa_user_sgpr_kernarg_preload_offset 0
		.amdhsa_user_sgpr_private_segment_size 0
		.amdhsa_uses_dynamic_stack 0
		.amdhsa_enable_private_segment 0
		.amdhsa_system_sgpr_workgroup_id_x 1
		.amdhsa_system_sgpr_workgroup_id_y 0
		.amdhsa_system_sgpr_workgroup_id_z 0
		.amdhsa_system_sgpr_workgroup_info 0
		.amdhsa_system_vgpr_workitem_id 2
		.amdhsa_next_free_vgpr 256
		.amdhsa_next_free_sgpr 102
		.amdhsa_accum_offset 256
		.amdhsa_reserve_vcc 1
		.amdhsa_float_round_mode_32 0
		.amdhsa_float_round_mode_16_64 0
		.amdhsa_float_denorm_mode_32 3
		.amdhsa_float_denorm_mode_16_64 3
		.amdhsa_dx10_clamp 1
		.amdhsa_ieee_mode 1
		.amdhsa_fp16_overflow 0
		.amdhsa_tg_split 0
		.amdhsa_exception_fp_ieee_invalid_op 0
		.amdhsa_exception_fp_denorm_src 0
		.amdhsa_exception_fp_ieee_div_zero 0
		.amdhsa_exception_fp_ieee_overflow 0
		.amdhsa_exception_fp_ieee_underflow 0
		.amdhsa_exception_fp_ieee_inexact 0
		.amdhsa_exception_int_div_zero 0
	.end_amdhsa_kernel

amdhsa.kernels:
  - .agpr_count:     0
    .args:
      - .offset:         0
        .size:           224
        .value_kind:     by_value
      - .offset:         224
        .size:           4
        .value_kind:     hidden_block_count_x
      - .offset:         228
        .size:           4
        .value_kind:     hidden_block_count_y
      - .offset:         232
        .size:           4
        .value_kind:     hidden_block_count_z
      - .offset:         236
        .size:           2
        .value_kind:     hidden_group_size_x
      - .offset:         238
        .size:           2
        .value_kind:     hidden_group_size_y
      - .offset:         240
        .size:           2
        .value_kind:     hidden_group_size_z
      - .offset:         242
        .size:           2
        .value_kind:     hidden_remainder_x
      - .offset:         244
        .size:           2
        .value_kind:     hidden_remainder_y
      - .offset:         246
        .size:           2
        .value_kind:     hidden_remainder_z
      - .offset:         264
        .size:           8
        .value_kind:     hidden_global_offset_x
      - .offset:         272
        .size:           8
        .value_kind:     hidden_global_offset_y
      - .offset:         280
        .size:           8
        .value_kind:     hidden_global_offset_z
      - .offset:         288
        .size:           2
        .value_kind:     hidden_grid_dims
      - .offset:         312
        .size:           8
        .value_kind:     hidden_multigrid_sync_arg
      - .offset:         344
        .size:           4
        .value_kind:     hidden_dynamic_lds_size
    .group_segment_fixed_size: 0
    .kernarg_segment_align: 8
    .kernarg_segment_size: 480
    .language:       OpenCL C
    .language_version:
      - 2
      - 0
    .max_flat_workgroup_size: 512
    .name:           _Z8yoco_fwd1P
    .private_segment_fixed_size: 0
    .sgpr_count:     108
    .sgpr_spill_count: 352
    .symbol:         _Z8yoco_fwd1P.kd
    .uniform_work_group_size: 1
    .uses_dynamic_stack: false
    .vgpr_count:     256
    .vgpr_spill_count: 0
    .wavefront_size: 64
